# grid barriers at seams 2-13 replaced by a two-level barrier (per-slot arrival counters, 8 collectors bump a top counter): less fan-in contention on one address
# speedup vs baseline: 1.0208x; 1.0076x over previous
.LBB0_185:
	s_or_b64 exec, exec, s[10:11]
	s_waitcnt lgkmcnt(0)
	v_readlane_b32 s2, v253, 4
	v_ashrrev_i32_e32 v83, 31, v82
	v_readlane_b32 s3, v253, 5
	s_nop 1
	v_lshl_add_u64 v[2:3], s[2:3], 0, v[82:83]
	v_cmp_eq_u64_e32 vcc, 0, v[2:3]
	s_and_saveexec_b64 s[2:3], vcc
	s_cbranch_execz .LBB0_187
	v_mov_b32_e32 v1, 0x3b0b000
	v_mov_b32_e32 v4, 0
	global_store_dword v1, v4, s[0:1] offset:256
	global_store_dword v1, v4, s[0:1] offset:320
	global_store_dword v1, v4, s[0:1] offset:324
	global_store_dword v1, v4, s[0:1] offset:328
	global_store_dword v1, v4, s[0:1] offset:332
	global_store_dword v1, v4, s[0:1] offset:336
	global_store_dword v1, v4, s[0:1] offset:340
	global_store_dword v1, v4, s[0:1] offset:344
	global_store_dword v1, v4, s[0:1] offset:348
	global_store_dword v1, v4, s[0:1] offset:384

.LBB0_954:
	v_readlane_b32 s0, v253, 0
	v_readlane_b32 s1, v253, 1
	s_cmp_gt_i32 s1, 3
	s_cselect_b64 s[0:1], -1, 0
	s_and_b64 s[2:3], s[68:69], s[0:1]
	s_andn2_b64 vcc, exec, s[2:3]
	s_cbranch_vccnz .LBB0_963
	v_readlane_b32 s2, v253, 22
	s_add_i32 s2, s2, 1
	v_cmp_eq_u32_e32 vcc, 0, v180
	s_waitcnt vmcnt(0)
	s_barrier
	v_writelane_b32 v253, s2, 22
	s_and_saveexec_b64 s[2:3], vcc
	s_cbranch_execz .LBB0_962
	s_cmp_eq_u32 s46, 0x100
	s_cbranch_scc0 .Lgb_orig_2
	v_readlane_b32 s100, v253, 32
	v_readlane_b32 s101, v253, 33
	s_mov_b32 s98, 1
	v_readlane_b32 s99, v253, 16
	s_nop 0
	s_and_b32 s99, s99, 7
	s_lshl_b32 s99, s99, 2
	v_mov_b32_e32 v0, s99
	v_mov_b32_e32 v1, 1
	buffer_wbl2 sc1
	s_waitcnt vmcnt(0)
	s_nop 4
	global_atomic_add v0, v1, s[100:101] offset:64
	v_readlane_b32 s99, v253, 16
	s_nop 0
	s_lshr_b32 s99, s99, 3
	s_cmp_eq_u32 s99, 0
	s_cbranch_scc0 .Lgb_wait_2
	s_lshl_b32 s99, s98, 5
.Lgb_cpoll_2:
	global_load_dword v1, v0, s[100:101] offset:64 sc1
	s_waitcnt vmcnt(0)
	v_cmp_le_u32_e32 vcc, s99, v1
	s_cbranch_vccnz .Lgb_cdone_2
	s_sleep 1
	s_branch .Lgb_cpoll_2
.Lgb_cdone_2:
	v_mov_b32_e32 v0, 0
	v_mov_b32_e32 v1, 1
	global_atomic_add v0, v1, s[100:101] offset:128
.Lgb_wait_2:
	s_lshl_b32 s98, s98, 3
	v_mov_b32_e32 v0, 0
.Lgb_poll_2:
	global_load_dword v1, v0, s[100:101] offset:128 sc1
	s_waitcnt vmcnt(0)
	v_cmp_le_u32_e32 vcc, s98, v1
	s_cbranch_vccnz .Lgb_done_2
	s_sleep 1
	s_branch .Lgb_poll_2
.Lgb_done_2:
	buffer_inv sc1
	s_branch .LBB0_962
.Lgb_orig_2:
	s_mov_b64 s[6:7], exec
	v_mbcnt_lo_u32_b32 v0, s6, 0
	v_mbcnt_hi_u32_b32 v0, s7, v0
	v_cmp_eq_u32_e32 vcc, 0, v0
	buffer_wbl2 sc1
	s_and_saveexec_b64 s[4:5], vcc
	s_cbranch_execz .LBB0_958
	s_bcnt1_i32_b64 s6, s[6:7]
	v_mov_b32_e32 v1, s6
	v_readlane_b32 s6, v253, 32
	v_mov_b32_e32 v0, 0
	v_readlane_b32 s7, v253, 33
	s_nop 4
	global_atomic_add v0, v1, s[6:7]

.LBB0_1284:
	v_readlane_b32 s0, v253, 0
	v_readlane_b32 s1, v253, 1
	s_cmp_gt_i32 s1, 4
	v_readlane_b32 s2, v253, 30
	s_cselect_b64 s[0:1], -1, 0
	v_readlane_b32 s3, v253, 31
	s_and_b64 s[2:3], s[2:3], s[0:1]
	s_andn2_b64 vcc, exec, s[2:3]
	s_cbranch_vccnz .LBB0_1293
	v_readlane_b32 s2, v253, 22
	s_add_i32 s2, s2, 1
	v_cmp_eq_u32_e32 vcc, 0, v180
	s_waitcnt vmcnt(0)
	s_barrier
	v_writelane_b32 v253, s2, 22
	s_and_saveexec_b64 s[2:3], vcc
	s_cbranch_execz .LBB0_1292
	s_cmp_eq_u32 s46, 0x100
	s_cbranch_scc0 .Lgb_orig_3
	v_readlane_b32 s100, v253, 32
	v_readlane_b32 s101, v253, 33
	s_mov_b32 s98, 2
	v_readlane_b32 s99, v253, 16
	s_nop 0
	s_and_b32 s99, s99, 7
	s_lshl_b32 s99, s99, 2
	v_mov_b32_e32 v0, s99
	v_mov_b32_e32 v1, 1
	buffer_wbl2 sc1
	s_waitcnt vmcnt(0)
	s_nop 4
	global_atomic_add v0, v1, s[100:101] offset:64
	v_readlane_b32 s99, v253, 16
	s_nop 0
	s_lshr_b32 s99, s99, 3
	s_cmp_eq_u32 s99, 0
	s_cbranch_scc0 .Lgb_wait_3
	s_lshl_b32 s99, s98, 5

.LBB0_1381:
	v_readlane_b32 s0, v253, 0
	v_readlane_b32 s1, v253, 1
	s_cmp_gt_i32 s1, 5
	s_cselect_b64 s[0:1], -1, 0
	s_and_b64 s[2:3], s[2:3], s[0:1]
	s_andn2_b64 vcc, exec, s[2:3]
	s_cbranch_vccnz .LBB0_1390
	v_readlane_b32 s2, v253, 22
	s_add_i32 s2, s2, 1
	v_cmp_eq_u32_e32 vcc, 0, v180
	s_waitcnt vmcnt(0) lgkmcnt(0)
	s_barrier
	v_writelane_b32 v253, s2, 22
	s_and_saveexec_b64 s[2:3], vcc
	s_cbranch_execz .LBB0_1389
	s_cmp_eq_u32 s46, 0x100
	s_cbranch_scc0 .Lgb_orig_4
	v_readlane_b32 s100, v253, 32
	v_readlane_b32 s101, v253, 33
	s_mov_b32 s98, 3
	v_readlane_b32 s99, v253, 16
	s_nop 0
	s_and_b32 s99, s99, 7
	s_lshl_b32 s99, s99, 2
	v_mov_b32_e32 v0, s99
	v_mov_b32_e32 v1, 1
	buffer_wbl2 sc1
	s_waitcnt vmcnt(0)
	s_nop 4
	global_atomic_add v0, v1, s[100:101] offset:64
	v_readlane_b32 s99, v253, 16
	s_nop 0
	s_lshr_b32 s99, s99, 3
	s_cmp_eq_u32 s99, 0
	s_cbranch_scc0 .Lgb_wait_4
	s_lshl_b32 s99, s98, 5

.LBB0_1411:
	v_readlane_b32 s0, v253, 0
	v_readlane_b32 s1, v253, 1
	s_cmp_gt_i32 s1, 6
	s_cselect_b64 s[4:5], -1, 0
	s_and_b64 s[0:1], s[2:3], s[4:5]
	s_andn2_b64 vcc, exec, s[0:1]
	s_cbranch_vccnz .LBB0_1420
	v_readlane_b32 s0, v253, 22
	s_add_i32 s0, s0, 1
	v_cmp_eq_u32_e32 vcc, 0, v180
	s_waitcnt vmcnt(0) lgkmcnt(0)
	s_barrier
	v_writelane_b32 v253, s0, 22
	s_and_saveexec_b64 s[0:1], vcc
	s_cbranch_execz .LBB0_1419
	s_cmp_eq_u32 s46, 0x100
	s_cbranch_scc0 .Lgb_orig_5
	v_readlane_b32 s100, v253, 32
	v_readlane_b32 s101, v253, 33
	s_mov_b32 s98, 4
	v_readlane_b32 s99, v253, 16
	s_nop 0
	s_and_b32 s99, s99, 7
	s_lshl_b32 s99, s99, 2
	v_mov_b32_e32 v0, s99
	v_mov_b32_e32 v1, 1
	buffer_wbl2 sc1
	s_waitcnt vmcnt(0)
	s_nop 4
	global_atomic_add v0, v1, s[100:101] offset:64
	v_readlane_b32 s99, v253, 16
	s_nop 0
	s_lshr_b32 s99, s99, 3
	s_cmp_eq_u32 s99, 0
	s_cbranch_scc0 .Lgb_wait_5
	s_lshl_b32 s99, s98, 5

.Lgb_orig_5:
	s_mov_b64 s[6:7], exec
	v_mbcnt_lo_u32_b32 v0, s6, 0
	v_mbcnt_hi_u32_b32 v0, s7, v0
	v_cmp_eq_u32_e32 vcc, 0, v0
	buffer_wbl2 sc1
	s_and_saveexec_b64 s[2:3], vcc
	s_cbranch_execz .LBB0_1415
	s_bcnt1_i32_b64 s6, s[6:7]
	v_mov_b32_e32 v1, s6
	v_readlane_b32 s6, v253, 32
	v_mov_b32_e32 v0, 0
	v_readlane_b32 s7, v253, 33
	s_nop 4
	global_atomic_add v0, v1, s[6:7]

.LBB0_1459:
	v_readlane_b32 s6, v253, 0
	v_readlane_b32 s7, v253, 1
	s_cmp_gt_i32 s7, 7
	s_cselect_b64 s[6:7], -1, 0
	s_and_b64 s[0:1], s[0:1], s[6:7]
	s_andn2_b64 vcc, exec, s[0:1]
	s_cbranch_vccnz .LBB0_1468
	v_readlane_b32 s0, v253, 22
	s_add_i32 s0, s0, 1
	v_cmp_eq_u32_e32 vcc, 0, v180
	s_waitcnt vmcnt(0) lgkmcnt(0)
	s_barrier
	v_writelane_b32 v253, s0, 22
	s_and_saveexec_b64 s[0:1], vcc
	s_cbranch_execz .LBB0_1467
	s_cmp_eq_u32 s46, 0x100
	s_cbranch_scc0 .Lgb_orig_6
	v_readlane_b32 s100, v253, 32
	v_readlane_b32 s101, v253, 33
	s_mov_b32 s98, 5
	v_readlane_b32 s99, v253, 16
	s_nop 0
	s_and_b32 s99, s99, 7
	s_lshl_b32 s99, s99, 2
	v_mov_b32_e32 v0, s99
	v_mov_b32_e32 v1, 1
	buffer_wbl2 sc1
	s_waitcnt vmcnt(0)
	s_nop 4
	global_atomic_add v0, v1, s[100:101] offset:64
	v_readlane_b32 s99, v253, 16
	s_nop 0
	s_lshr_b32 s99, s99, 3
	s_cmp_eq_u32 s99, 0
	s_cbranch_scc0 .Lgb_wait_6
	s_lshl_b32 s99, s98, 5

.Lgb_orig_6:
	s_mov_b64 s[10:11], exec
	v_mbcnt_lo_u32_b32 v0, s10, 0
	v_mbcnt_hi_u32_b32 v0, s11, v0
	v_cmp_eq_u32_e32 vcc, 0, v0
	buffer_wbl2 sc1
	s_and_saveexec_b64 s[8:9], vcc
	s_cbranch_execz .LBB0_1463
	s_bcnt1_i32_b64 s10, s[10:11]
	v_mov_b32_e32 v1, s10
	v_readlane_b32 s10, v253, 32
	v_mov_b32_e32 v0, 0
	v_readlane_b32 s11, v253, 33
	s_nop 4
	global_atomic_add v0, v1, s[10:11]

.LBB0_1489:
	v_readlane_b32 s6, v253, 0
	v_readlane_b32 s7, v253, 1
	s_cmp_gt_i32 s7, 8
	s_cselect_b64 s[6:7], -1, 0
	s_and_b64 s[0:1], s[0:1], s[6:7]
	s_andn2_b64 vcc, exec, s[0:1]
	s_cbranch_vccnz .LBB0_1498
	v_readlane_b32 s0, v253, 22
	s_add_i32 s0, s0, 1
	v_cmp_eq_u32_e32 vcc, 0, v180
	s_waitcnt vmcnt(0) lgkmcnt(0)
	s_barrier
	v_writelane_b32 v253, s0, 22
	s_and_saveexec_b64 s[0:1], vcc
	s_cbranch_execz .LBB0_1497
	s_cmp_eq_u32 s46, 0x100
	s_cbranch_scc0 .Lgb_orig_7
	v_readlane_b32 s100, v253, 32
	v_readlane_b32 s101, v253, 33
	s_mov_b32 s98, 6
	v_readlane_b32 s99, v253, 16
	s_nop 0
	s_and_b32 s99, s99, 7
	s_lshl_b32 s99, s99, 2
	v_mov_b32_e32 v0, s99
	v_mov_b32_e32 v1, 1
	buffer_wbl2 sc1
	s_waitcnt vmcnt(0)
	s_nop 4
	global_atomic_add v0, v1, s[100:101] offset:64
	v_readlane_b32 s99, v253, 16
	s_nop 0
	s_lshr_b32 s99, s99, 3
	s_cmp_eq_u32 s99, 0
	s_cbranch_scc0 .Lgb_wait_7
	s_lshl_b32 s99, s98, 5

.LBB0_1541:
	v_readlane_b32 s6, v253, 0
	v_readlane_b32 s7, v253, 1
	s_cmp_gt_i32 s7, 9
	s_cselect_b64 s[6:7], -1, 0
	s_and_b64 s[0:1], s[0:1], s[6:7]
	s_andn2_b64 vcc, exec, s[0:1]
	s_cbranch_vccnz .LBB0_1550
	v_readlane_b32 s0, v253, 22
	s_add_i32 s0, s0, 1
	v_cmp_eq_u32_e32 vcc, 0, v180
	s_waitcnt vmcnt(0) lgkmcnt(0)
	s_barrier
	v_writelane_b32 v253, s0, 22
	s_and_saveexec_b64 s[0:1], vcc
	s_cbranch_execz .LBB0_1549
	s_cmp_eq_u32 s46, 0x100
	s_cbranch_scc0 .Lgb_orig_8
	v_readlane_b32 s100, v253, 32
	v_readlane_b32 s101, v253, 33
	s_mov_b32 s98, 7
	v_readlane_b32 s99, v253, 16
	s_nop 0
	s_and_b32 s99, s99, 7
	s_lshl_b32 s99, s99, 2
	v_mov_b32_e32 v0, s99
	v_mov_b32_e32 v1, 1
	buffer_wbl2 sc1
	s_waitcnt vmcnt(0)
	s_nop 4
	global_atomic_add v0, v1, s[100:101] offset:64
	v_readlane_b32 s99, v253, 16
	s_nop 0
	s_lshr_b32 s99, s99, 3
	s_cmp_eq_u32 s99, 0
	s_cbranch_scc0 .Lgb_wait_8
	s_lshl_b32 s99, s98, 5

.LBB0_1733:
	v_readlane_b32 s0, v253, 0
	v_readlane_b32 s1, v253, 1
	s_cmp_gt_i32 s1, 10
	s_cselect_b64 s[6:7], -1, 0
	s_and_b64 s[0:1], s[14:15], s[6:7]
	s_andn2_b64 vcc, exec, s[0:1]
	s_cbranch_vccnz .LBB0_1742
	v_readlane_b32 s0, v253, 22
	s_add_i32 s0, s0, 1
	v_cmp_eq_u32_e32 vcc, 0, v180
	s_waitcnt vmcnt(0) lgkmcnt(0)
	s_barrier
	v_writelane_b32 v253, s0, 22
	s_and_saveexec_b64 s[0:1], vcc
	s_cbranch_execz .LBB0_1741
	s_cmp_eq_u32 s46, 0x100
	s_cbranch_scc0 .Lgb_orig_9
	v_readlane_b32 s100, v253, 32
	v_readlane_b32 s101, v253, 33
	s_mov_b32 s98, 8
	v_readlane_b32 s99, v253, 16
	s_nop 0
	s_and_b32 s99, s99, 7
	s_lshl_b32 s99, s99, 2
	v_mov_b32_e32 v0, s99
	v_mov_b32_e32 v1, 1
	buffer_wbl2 sc1
	s_waitcnt vmcnt(0)
	s_nop 4
	global_atomic_add v0, v1, s[100:101] offset:64
	v_readlane_b32 s99, v253, 16
	s_nop 0
	s_lshr_b32 s99, s99, 3
	s_cmp_eq_u32 s99, 0
	s_cbranch_scc0 .Lgb_wait_9
	s_lshl_b32 s99, s98, 5

.LBB0_1810:
	v_readlane_b32 s6, v253, 0
	v_readlane_b32 s7, v253, 1
	s_cmp_gt_i32 s7, 11
	s_cselect_b64 s[6:7], -1, 0
	s_and_b64 s[0:1], s[0:1], s[6:7]
	s_andn2_b64 vcc, exec, s[0:1]
	s_cbranch_vccnz .LBB0_1819
	v_readlane_b32 s0, v253, 22
	s_add_i32 s0, s0, 1
	v_cmp_eq_u32_e32 vcc, 0, v180
	s_waitcnt vmcnt(0) lgkmcnt(0)
	s_barrier
	v_writelane_b32 v253, s0, 22
	s_and_saveexec_b64 s[0:1], vcc
	s_cbranch_execz .LBB0_1818
	s_cmp_eq_u32 s46, 0x100
	s_cbranch_scc0 .Lgb_orig_10
	v_readlane_b32 s100, v253, 32
	v_readlane_b32 s101, v253, 33
	s_mov_b32 s98, 9
	v_readlane_b32 s99, v253, 16
	s_nop 0
	s_and_b32 s99, s99, 7
	s_lshl_b32 s99, s99, 2
	v_mov_b32_e32 v0, s99
	v_mov_b32_e32 v1, 1
	buffer_wbl2 sc1
	s_waitcnt vmcnt(0)
	s_nop 4
	global_atomic_add v0, v1, s[100:101] offset:64
	v_readlane_b32 s99, v253, 16
	s_nop 0
	s_lshr_b32 s99, s99, 3
	s_cmp_eq_u32 s99, 0
	s_cbranch_scc0 .Lgb_wait_10
	s_lshl_b32 s99, s98, 5

.LBB0_1858:
	v_readlane_b32 s6, v253, 0
	v_readlane_b32 s7, v253, 1
	s_cmp_gt_i32 s7, 12
	s_cselect_b64 s[6:7], -1, 0
	s_and_b64 s[0:1], s[0:1], s[6:7]
	s_andn2_b64 vcc, exec, s[0:1]
	s_cbranch_vccnz .LBB0_1867
	v_readlane_b32 s0, v253, 22
	s_add_i32 s0, s0, 1
	v_cmp_eq_u32_e32 vcc, 0, v180
	s_waitcnt vmcnt(0) lgkmcnt(0)
	s_barrier
	v_writelane_b32 v253, s0, 22
	s_and_saveexec_b64 s[0:1], vcc
	s_cbranch_execz .LBB0_1866
	s_cmp_eq_u32 s46, 0x100
	s_cbranch_scc0 .Lgb_orig_11
	v_readlane_b32 s100, v253, 32
	v_readlane_b32 s101, v253, 33
	s_mov_b32 s98, 10
	v_readlane_b32 s99, v253, 16
	s_nop 0
	s_and_b32 s99, s99, 7
	s_lshl_b32 s99, s99, 2
	v_mov_b32_e32 v0, s99
	v_mov_b32_e32 v1, 1
	buffer_wbl2 sc1
	s_waitcnt vmcnt(0)
	s_nop 4
	global_atomic_add v0, v1, s[100:101] offset:64
	v_readlane_b32 s99, v253, 16
	s_nop 0
	s_lshr_b32 s99, s99, 3
	s_cmp_eq_u32 s99, 0
	s_cbranch_scc0 .Lgb_wait_11
	s_lshl_b32 s99, s98, 5

.LBB0_1888:
	v_readlane_b32 s6, v253, 0
	v_readlane_b32 s7, v253, 1
	s_cmp_gt_i32 s7, 13
	s_cselect_b64 s[6:7], -1, 0
	s_and_b64 s[0:1], s[0:1], s[6:7]
	s_andn2_b64 vcc, exec, s[0:1]
	s_cbranch_vccnz .LBB0_1897
	v_readlane_b32 s0, v253, 22
	s_add_i32 s0, s0, 1
	v_cmp_eq_u32_e32 vcc, 0, v180
	s_waitcnt vmcnt(0) lgkmcnt(0)
	s_barrier
	v_writelane_b32 v253, s0, 22
	s_and_saveexec_b64 s[0:1], vcc
	s_cbranch_execz .LBB0_1896
	s_cmp_eq_u32 s46, 0x100
	s_cbranch_scc0 .Lgb_orig_12
	v_readlane_b32 s100, v253, 32
	v_readlane_b32 s101, v253, 33
	s_mov_b32 s98, 11
	v_readlane_b32 s99, v253, 16
	s_nop 0
	s_and_b32 s99, s99, 7
	s_lshl_b32 s99, s99, 2
	v_mov_b32_e32 v0, s99
	v_mov_b32_e32 v1, 1
	buffer_wbl2 sc1
	s_waitcnt vmcnt(0)
	s_nop 4
	global_atomic_add v0, v1, s[100:101] offset:64
	v_readlane_b32 s99, v253, 16
	s_nop 0
	s_lshr_b32 s99, s99, 3
	s_cmp_eq_u32 s99, 0
	s_cbranch_scc0 .Lgb_wait_12
	s_lshl_b32 s99, s98, 5

.LBB0_1940:
	v_readlane_b32 s2, v253, 0
	v_readlane_b32 s3, v253, 1
	s_cmp_gt_i32 s3, 14
	s_cselect_b64 s[2:3], -1, 0
	s_and_b64 s[0:1], s[0:1], s[2:3]
	s_andn2_b64 vcc, exec, s[0:1]
	s_cbranch_vccnz .LBB0_1949
	v_cmp_eq_u32_e32 vcc, 0, v180
	s_waitcnt vmcnt(0) lgkmcnt(0)
	s_barrier
	s_and_saveexec_b64 s[0:1], vcc
	s_cbranch_execz .LBB0_1948
	s_cmp_eq_u32 s46, 0x100
	s_cbranch_scc0 .Lgb_orig_13
	v_readlane_b32 s100, v253, 32
	v_readlane_b32 s101, v253, 33
	s_mov_b32 s98, 12
	v_readlane_b32 s99, v253, 16
	s_nop 0
	s_and_b32 s99, s99, 7
	s_lshl_b32 s99, s99, 2
	v_mov_b32_e32 v0, s99
	v_mov_b32_e32 v1, 1
	buffer_wbl2 sc1
	s_waitcnt vmcnt(0)
	s_nop 4
	global_atomic_add v0, v1, s[100:101] offset:64
	v_readlane_b32 s99, v253, 16
	s_nop 0
	s_lshr_b32 s99, s99, 3
	s_cmp_eq_u32 s99, 0
	s_cbranch_scc0 .Lgb_wait_13
	s_lshl_b32 s99, s98, 5
